# carry scan inner loop rewritten by hand: 16-deep software-pipelined loads, scalar pointer stepping (f32 math unchanged)
# speedup vs baseline: 1.0045x; 1.0045x over previous
; __device__ __forceinline__ unsigned cvt_pk_bf16(float lo, float hi) { const f32x2 v = {lo, hi}; const bf16x2_t b = __builtin_convertvector(v, bf16x2_t); return __builtin_bit_cast(unsigned, b); }
; #define Sb WSP(float, WS_H)
; __global__ void __launch_bounds__(NTHREADS, 2) mega(Args a) {
;     ...
;                     const float ar = A16[((g * 2 + dir) * 64 + lane) * 2], ai = A16[((g * 2 + dir) * 64 + lane) * 2 + 1];
;                     float hr = 0.f, hi = 0.f;
;                     const size_t rbase = (size_t)g * NROW + (size_t)b * NC;
;                     for (int c0 = 0; c0 < NC; c0 += 16) {
;                         float sr[16], si[16];
; #pragma unroll
;                         for (int e = 0; e < 16; ++e) { const int c = dir ? NC - 1 - (c0 + e) : c0 + e; const float* sp = Sb + (rbase + c) * 256 + dir * 128 + lane; sr[e] = sp[0]; si[e] = sp[64]; }
; #pragma unroll
;                         for (int e = 0; e < 16; ++e) { const int c = dir ? NC - 1 - (c0 + e) : c0 + e; bf16_t* hp = SSMA + (rbase + c) * 512 + 256 + dir * 128 + lane;
;                             hp[0] = (bf16_t)(cvt_pk_bf16(hr, 0.f) & 0xffffu); hp[64] = (bf16_t)(cvt_pk_bf16(hi, 0.f) & 0xffffu);
;                             const float t = ar * hr - ai * hi + sr[e]; hi = ar * hi + ai * hr + si[e]; hr = t; }
.LBB0_508:
	v_lshlrev_b32_e32 v12, 2, v2
	v_lshlrev_b32_e32 v13, 1, v2
	s_movk_i32 s18, 0x400
	s_and_b64 s[4:5], s[66:67], exec
	s_cselect_b32 s2, 0, s79
	s_cselect_b32 s44, s18, 0xfffffc00
	s_cselect_b32 s45, 0, -1
	s_add_u32 s4, s76, s2
	s_addc_u32 s5, s77, 0
	s_lshl_b64 s[4:5], s[4:5], 10
	s_add_u32 s4, s4, s96
	s_addc_u32 s5, s5, s97
	s_lshl_b32 s3, s30, 2
	s_add_u32 s40, s4, s3
	s_addc_u32 s41, s5, 0
	s_add_u32 s40, s40, 0x6f00000
	s_addc_u32 s41, s41, 0
	s_lshl_b32 s3, s30, 1
	s_add_u32 s42, s4, s3
	s_addc_u32 s43, s5, 0
	s_add_u32 s42, s42, 0x10f00000
	s_addc_u32 s43, s43, 0
	s_lshr_b32 s46, s70, 4
	global_load_dword v16, v12, s[40:41]
	global_load_dword v17, v12, s[40:41] offset:256
	s_add_u32 s40, s40, s44
	s_addc_u32 s41, s41, s45
	global_load_dword v18, v12, s[40:41]
	global_load_dword v19, v12, s[40:41] offset:256
	s_add_u32 s40, s40, s44
	s_addc_u32 s41, s41, s45
	global_load_dword v20, v12, s[40:41]
	global_load_dword v21, v12, s[40:41] offset:256
	s_add_u32 s40, s40, s44
	s_addc_u32 s41, s41, s45
	global_load_dword v22, v12, s[40:41]
	global_load_dword v23, v12, s[40:41] offset:256
	s_add_u32 s40, s40, s44
	s_addc_u32 s41, s41, s45
	global_load_dword v24, v12, s[40:41]
	global_load_dword v25, v12, s[40:41] offset:256
	s_add_u32 s40, s40, s44
	s_addc_u32 s41, s41, s45
	global_load_dword v26, v12, s[40:41]
	global_load_dword v27, v12, s[40:41] offset:256
	s_add_u32 s40, s40, s44
	s_addc_u32 s41, s41, s45
	global_load_dword v28, v12, s[40:41]
	global_load_dword v29, v12, s[40:41] offset:256
	s_add_u32 s40, s40, s44
	s_addc_u32 s41, s41, s45
	global_load_dword v30, v12, s[40:41]
	global_load_dword v31, v12, s[40:41] offset:256
	s_add_u32 s40, s40, s44
	s_addc_u32 s41, s41, s45
	global_load_dword v32, v12, s[40:41]
	global_load_dword v33, v12, s[40:41] offset:256
	s_add_u32 s40, s40, s44
	s_addc_u32 s41, s41, s45
	global_load_dword v34, v12, s[40:41]
	global_load_dword v35, v12, s[40:41] offset:256
	s_add_u32 s40, s40, s44
	s_addc_u32 s41, s41, s45
	global_load_dword v36, v12, s[40:41]
	global_load_dword v37, v12, s[40:41] offset:256
	s_add_u32 s40, s40, s44
	s_addc_u32 s41, s41, s45
	global_load_dword v38, v12, s[40:41]
	global_load_dword v39, v12, s[40:41] offset:256
	s_add_u32 s40, s40, s44
	s_addc_u32 s41, s41, s45
	global_load_dword v40, v12, s[40:41]
	global_load_dword v41, v12, s[40:41] offset:256
	s_add_u32 s40, s40, s44
	s_addc_u32 s41, s41, s45
	global_load_dword v42, v12, s[40:41]
	global_load_dword v43, v12, s[40:41] offset:256
	s_add_u32 s40, s40, s44
	s_addc_u32 s41, s41, s45
	global_load_dword v44, v12, s[40:41]
	global_load_dword v45, v12, s[40:41] offset:256
	s_add_u32 s40, s40, s44
	s_addc_u32 s41, s41, s45
	global_load_dword v46, v12, s[40:41]
	global_load_dword v47, v12, s[40:41] offset:256
	s_add_u32 s40, s40, s44
	s_addc_u32 s41, s41, s45
	v_cvt_pk_bf16_f32 v48, v14, v14
	v_cvt_pk_bf16_f32 v49, v15, v15
	global_store_short v13, v48, s[42:43] offset:512
	global_store_short v13, v49, s[42:43] offset:640
	s_add_u32 s42, s42, s44
	s_addc_u32 s43, s43, s45
	v_mul_f32_e32 v50, v6, v14
	v_mul_f32_e32 v51, v6, v15
	v_fma_f32 v52, v4, v14, -v51
	v_fma_f32 v53, v4, v15, v50
	s_waitcnt vmcnt(32)
	v_add_f32_e32 v14, v52, v16
	v_add_f32_e32 v15, v53, v17
	global_load_dword v16, v12, s[40:41]
	global_load_dword v17, v12, s[40:41] offset:256
	s_add_u32 s40, s40, s44
	s_addc_u32 s41, s41, s45
	v_cvt_pk_bf16_f32 v48, v14, v14
	v_cvt_pk_bf16_f32 v49, v15, v15
	global_store_short v13, v48, s[42:43] offset:512
	global_store_short v13, v49, s[42:43] offset:640
	s_add_u32 s42, s42, s44
	s_addc_u32 s43, s43, s45
	v_mul_f32_e32 v50, v6, v14
	v_mul_f32_e32 v51, v6, v15
	v_fma_f32 v52, v4, v14, -v51
	v_fma_f32 v53, v4, v15, v50
	s_waitcnt vmcnt(34)
	v_add_f32_e32 v14, v52, v18
	v_add_f32_e32 v15, v53, v19
	global_load_dword v18, v12, s[40:41]
	global_load_dword v19, v12, s[40:41] offset:256
	s_add_u32 s40, s40, s44
	s_addc_u32 s41, s41, s45
	v_cvt_pk_bf16_f32 v48, v14, v14
	v_cvt_pk_bf16_f32 v49, v15, v15
	global_store_short v13, v48, s[42:43] offset:512
	global_store_short v13, v49, s[42:43] offset:640
	s_add_u32 s42, s42, s44
	s_addc_u32 s43, s43, s45
	v_mul_f32_e32 v50, v6, v14
	v_mul_f32_e32 v51, v6, v15
	v_fma_f32 v52, v4, v14, -v51
	v_fma_f32 v53, v4, v15, v50
	s_waitcnt vmcnt(36)
	v_add_f32_e32 v14, v52, v20
	v_add_f32_e32 v15, v53, v21
	global_load_dword v20, v12, s[40:41]
	global_load_dword v21, v12, s[40:41] offset:256
	s_add_u32 s40, s40, s44
	s_addc_u32 s41, s41, s45
	v_cvt_pk_bf16_f32 v48, v14, v14
	v_cvt_pk_bf16_f32 v49, v15, v15
	global_store_short v13, v48, s[42:43] offset:512
	global_store_short v13, v49, s[42:43] offset:640
	s_add_u32 s42, s42, s44
	s_addc_u32 s43, s43, s45
	v_mul_f32_e32 v50, v6, v14
	v_mul_f32_e32 v51, v6, v15
	v_fma_f32 v52, v4, v14, -v51
	v_fma_f32 v53, v4, v15, v50
	s_waitcnt vmcnt(38)
	v_add_f32_e32 v14, v52, v22
	v_add_f32_e32 v15, v53, v23
	global_load_dword v22, v12, s[40:41]
	global_load_dword v23, v12, s[40:41] offset:256
	s_add_u32 s40, s40, s44
	s_addc_u32 s41, s41, s45
	v_cvt_pk_bf16_f32 v48, v14, v14
	v_cvt_pk_bf16_f32 v49, v15, v15
	global_store_short v13, v48, s[42:43] offset:512
	global_store_short v13, v49, s[42:43] offset:640
	s_add_u32 s42, s42, s44
	s_addc_u32 s43, s43, s45
	v_mul_f32_e32 v50, v6, v14
	v_mul_f32_e32 v51, v6, v15
	v_fma_f32 v52, v4, v14, -v51
	v_fma_f32 v53, v4, v15, v50
	s_waitcnt vmcnt(40)
; __device__ __forceinline__ unsigned cvt_pk_bf16(float lo, float hi) { const f32x2 v = {lo, hi}; const bf16x2_t b = __builtin_convertvector(v, bf16x2_t); return __builtin_bit_cast(unsigned, b); }
; #define Sb WSP(float, WS_H)
; __global__ void __launch_bounds__(NTHREADS, 2) mega(Args a) {
;     ...
;                     for (int c0 = 0; c0 < NC; c0 += 16) {
;                         float sr[16], si[16];
; #pragma unroll
;                         for (int e = 0; e < 16; ++e) { const int c = dir ? NC - 1 - (c0 + e) : c0 + e; const float* sp = Sb + (rbase + c) * 256 + dir * 128 + lane; sr[e] = sp[0]; si[e] = sp[64]; }
; #pragma unroll
;                         for (int e = 0; e < 16; ++e) { const int c = dir ? NC - 1 - (c0 + e) : c0 + e; bf16_t* hp = SSMA + (rbase + c) * 512 + 256 + dir * 128 + lane;
;                             hp[0] = (bf16_t)(cvt_pk_bf16(hr, 0.f) & 0xffffu); hp[64] = (bf16_t)(cvt_pk_bf16(hi, 0.f) & 0xffffu);
;                             const float t = ar * hr - ai * hi + sr[e]; hi = ar * hi + ai * hr + si[e]; hr = t; }
	v_add_f32_e32 v14, v52, v24
	v_add_f32_e32 v15, v53, v25
	global_load_dword v24, v12, s[40:41]
	global_load_dword v25, v12, s[40:41] offset:256
	s_add_u32 s40, s40, s44
	s_addc_u32 s41, s41, s45
	v_cvt_pk_bf16_f32 v48, v14, v14
	v_cvt_pk_bf16_f32 v49, v15, v15
	global_store_short v13, v48, s[42:43] offset:512
	global_store_short v13, v49, s[42:43] offset:640
	s_add_u32 s42, s42, s44
	s_addc_u32 s43, s43, s45
	v_mul_f32_e32 v50, v6, v14
	v_mul_f32_e32 v51, v6, v15
	v_fma_f32 v52, v4, v14, -v51
	v_fma_f32 v53, v4, v15, v50
	s_waitcnt vmcnt(42)
	v_add_f32_e32 v14, v52, v26
	v_add_f32_e32 v15, v53, v27
	global_load_dword v26, v12, s[40:41]
	global_load_dword v27, v12, s[40:41] offset:256
	s_add_u32 s40, s40, s44
	s_addc_u32 s41, s41, s45
	v_cvt_pk_bf16_f32 v48, v14, v14
	v_cvt_pk_bf16_f32 v49, v15, v15
	global_store_short v13, v48, s[42:43] offset:512
	global_store_short v13, v49, s[42:43] offset:640
	s_add_u32 s42, s42, s44
	s_addc_u32 s43, s43, s45
	v_mul_f32_e32 v50, v6, v14
	v_mul_f32_e32 v51, v6, v15
	v_fma_f32 v52, v4, v14, -v51
	v_fma_f32 v53, v4, v15, v50
	s_waitcnt vmcnt(44)
	v_add_f32_e32 v14, v52, v28
	v_add_f32_e32 v15, v53, v29
	global_load_dword v28, v12, s[40:41]
	global_load_dword v29, v12, s[40:41] offset:256
	s_add_u32 s40, s40, s44
	s_addc_u32 s41, s41, s45
	v_cvt_pk_bf16_f32 v48, v14, v14
	v_cvt_pk_bf16_f32 v49, v15, v15
	global_store_short v13, v48, s[42:43] offset:512
	global_store_short v13, v49, s[42:43] offset:640
	s_add_u32 s42, s42, s44
	s_addc_u32 s43, s43, s45
	v_mul_f32_e32 v50, v6, v14
	v_mul_f32_e32 v51, v6, v15
	v_fma_f32 v52, v4, v14, -v51
	v_fma_f32 v53, v4, v15, v50
	s_waitcnt vmcnt(46)
	v_add_f32_e32 v14, v52, v30
	v_add_f32_e32 v15, v53, v31
	global_load_dword v30, v12, s[40:41]
	global_load_dword v31, v12, s[40:41] offset:256
	s_add_u32 s40, s40, s44
	s_addc_u32 s41, s41, s45
	v_cvt_pk_bf16_f32 v48, v14, v14
	v_cvt_pk_bf16_f32 v49, v15, v15
	global_store_short v13, v48, s[42:43] offset:512
	global_store_short v13, v49, s[42:43] offset:640
	s_add_u32 s42, s42, s44
	s_addc_u32 s43, s43, s45
	v_mul_f32_e32 v50, v6, v14
	v_mul_f32_e32 v51, v6, v15
	v_fma_f32 v52, v4, v14, -v51
	v_fma_f32 v53, v4, v15, v50
	s_waitcnt vmcnt(48)
	v_add_f32_e32 v14, v52, v32
	v_add_f32_e32 v15, v53, v33
	global_load_dword v32, v12, s[40:41]
	global_load_dword v33, v12, s[40:41] offset:256
	s_add_u32 s40, s40, s44
	s_addc_u32 s41, s41, s45
	v_cvt_pk_bf16_f32 v48, v14, v14
	v_cvt_pk_bf16_f32 v49, v15, v15
	global_store_short v13, v48, s[42:43] offset:512
	global_store_short v13, v49, s[42:43] offset:640
	s_add_u32 s42, s42, s44
	s_addc_u32 s43, s43, s45
	v_mul_f32_e32 v50, v6, v14
	v_mul_f32_e32 v51, v6, v15
	v_fma_f32 v52, v4, v14, -v51
	v_fma_f32 v53, v4, v15, v50
	s_waitcnt vmcnt(50)
	v_add_f32_e32 v14, v52, v34
	v_add_f32_e32 v15, v53, v35
	global_load_dword v34, v12, s[40:41]
	global_load_dword v35, v12, s[40:41] offset:256
	s_add_u32 s40, s40, s44
	s_addc_u32 s41, s41, s45
	v_cvt_pk_bf16_f32 v48, v14, v14
	v_cvt_pk_bf16_f32 v49, v15, v15
	global_store_short v13, v48, s[42:43] offset:512
	global_store_short v13, v49, s[42:43] offset:640
	s_add_u32 s42, s42, s44
	s_addc_u32 s43, s43, s45
	v_mul_f32_e32 v50, v6, v14
	v_mul_f32_e32 v51, v6, v15
	v_fma_f32 v52, v4, v14, -v51
	v_fma_f32 v53, v4, v15, v50
	s_waitcnt vmcnt(52)
	v_add_f32_e32 v14, v52, v36
	v_add_f32_e32 v15, v53, v37
	global_load_dword v36, v12, s[40:41]
	global_load_dword v37, v12, s[40:41] offset:256
	s_add_u32 s40, s40, s44
	s_addc_u32 s41, s41, s45
	v_cvt_pk_bf16_f32 v48, v14, v14
	v_cvt_pk_bf16_f32 v49, v15, v15
	global_store_short v13, v48, s[42:43] offset:512
	global_store_short v13, v49, s[42:43] offset:640
	s_add_u32 s42, s42, s44
	s_addc_u32 s43, s43, s45
	v_mul_f32_e32 v50, v6, v14
	v_mul_f32_e32 v51, v6, v15
	v_fma_f32 v52, v4, v14, -v51
	v_fma_f32 v53, v4, v15, v50
	s_waitcnt vmcnt(54)
	v_add_f32_e32 v14, v52, v38
	v_add_f32_e32 v15, v53, v39
	global_load_dword v38, v12, s[40:41]
	global_load_dword v39, v12, s[40:41] offset:256
	s_add_u32 s40, s40, s44
	s_addc_u32 s41, s41, s45
	v_cvt_pk_bf16_f32 v48, v14, v14
	v_cvt_pk_bf16_f32 v49, v15, v15
	global_store_short v13, v48, s[42:43] offset:512
	global_store_short v13, v49, s[42:43] offset:640
	s_add_u32 s42, s42, s44
	s_addc_u32 s43, s43, s45
	v_mul_f32_e32 v50, v6, v14
	v_mul_f32_e32 v51, v6, v15
	v_fma_f32 v52, v4, v14, -v51
	v_fma_f32 v53, v4, v15, v50
	s_waitcnt vmcnt(56)
	v_add_f32_e32 v14, v52, v40
	v_add_f32_e32 v15, v53, v41
	global_load_dword v40, v12, s[40:41]
	global_load_dword v41, v12, s[40:41] offset:256
	s_add_u32 s40, s40, s44
	s_addc_u32 s41, s41, s45
	v_cvt_pk_bf16_f32 v48, v14, v14
	v_cvt_pk_bf16_f32 v49, v15, v15
	global_store_short v13, v48, s[42:43] offset:512
	global_store_short v13, v49, s[42:43] offset:640
	s_add_u32 s42, s42, s44
	s_addc_u32 s43, s43, s45
	v_mul_f32_e32 v50, v6, v14
	v_mul_f32_e32 v51, v6, v15
	v_fma_f32 v52, v4, v14, -v51
	v_fma_f32 v53, v4, v15, v50
	s_waitcnt vmcnt(58)
	v_add_f32_e32 v14, v52, v42
	v_add_f32_e32 v15, v53, v43
	global_load_dword v42, v12, s[40:41]
	global_load_dword v43, v12, s[40:41] offset:256
	s_add_u32 s40, s40, s44
	s_addc_u32 s41, s41, s45
	v_cvt_pk_bf16_f32 v48, v14, v14
	v_cvt_pk_bf16_f32 v49, v15, v15
	global_store_short v13, v48, s[42:43] offset:512
	global_store_short v13, v49, s[42:43] offset:640
	s_add_u32 s42, s42, s44
	s_addc_u32 s43, s43, s45
	v_mul_f32_e32 v50, v6, v14
	v_mul_f32_e32 v51, v6, v15
	v_fma_f32 v52, v4, v14, -v51
	v_fma_f32 v53, v4, v15, v50
	s_waitcnt vmcnt(60)
	v_add_f32_e32 v14, v52, v44
	v_add_f32_e32 v15, v53, v45
	global_load_dword v44, v12, s[40:41]
	global_load_dword v45, v12, s[40:41] offset:256
	s_add_u32 s40, s40, s44
	s_addc_u32 s41, s41, s45
	v_cvt_pk_bf16_f32 v48, v14, v14
	v_cvt_pk_bf16_f32 v49, v15, v15
	global_store_short v13, v48, s[42:43] offset:512
	global_store_short v13, v49, s[42:43] offset:640
	s_add_u32 s42, s42, s44
	s_addc_u32 s43, s43, s45
	v_mul_f32_e32 v50, v6, v14
	v_mul_f32_e32 v51, v6, v15
	v_fma_f32 v52, v4, v14, -v51
	v_fma_f32 v53, v4, v15, v50
	s_waitcnt vmcnt(62)
	v_add_f32_e32 v14, v52, v46
	v_add_f32_e32 v15, v53, v47
	global_load_dword v46, v12, s[40:41]
	global_load_dword v47, v12, s[40:41] offset:256
	s_add_u32 s40, s40, s44
	s_addc_u32 s41, s41, s45
	s_sub_u32 s46, s46, 1
	s_cmp_eq_u32 s46, 0
	s_cbranch_scc1 .Lscan_done
; __device__ __forceinline__ unsigned cvt_pk_bf16(float lo, float hi) { const f32x2 v = {lo, hi}; const bf16x2_t b = __builtin_convertvector(v, bf16x2_t); return __builtin_bit_cast(unsigned, b); }
; #define Sb WSP(float, WS_H)
; __global__ void __launch_bounds__(NTHREADS, 2) mega(Args a) {
;     ...
;                     for (int c0 = 0; c0 < NC; c0 += 16) {
;                         float sr[16], si[16];
; #pragma unroll
;                         for (int e = 0; e < 16; ++e) { const int c = dir ? NC - 1 - (c0 + e) : c0 + e; const float* sp = Sb + (rbase + c) * 256 + dir * 128 + lane; sr[e] = sp[0]; si[e] = sp[64]; }
; #pragma unroll
;                         for (int e = 0; e < 16; ++e) { const int c = dir ? NC - 1 - (c0 + e) : c0 + e; bf16_t* hp = SSMA + (rbase + c) * 512 + 256 + dir * 128 + lane;
;                             hp[0] = (bf16_t)(cvt_pk_bf16(hr, 0.f) & 0xffffu); hp[64] = (bf16_t)(cvt_pk_bf16(hi, 0.f) & 0xffffu);
;                             const float t = ar * hr - ai * hi + sr[e]; hi = ar * hi + ai * hr + si[e]; hr = t; }
.Lscan_loop:
	v_cvt_pk_bf16_f32 v48, v14, v14
	v_cvt_pk_bf16_f32 v49, v15, v15
	global_store_short v13, v48, s[42:43] offset:512
	global_store_short v13, v49, s[42:43] offset:640
	s_add_u32 s42, s42, s44
	s_addc_u32 s43, s43, s45
	v_mul_f32_e32 v50, v6, v14
	v_mul_f32_e32 v51, v6, v15
	v_fma_f32 v52, v4, v14, -v51
	v_fma_f32 v53, v4, v15, v50
	s_waitcnt vmcnt(62)
	v_add_f32_e32 v14, v52, v16
	v_add_f32_e32 v15, v53, v17
	global_load_dword v16, v12, s[40:41]
	global_load_dword v17, v12, s[40:41] offset:256
	s_add_u32 s40, s40, s44
	s_addc_u32 s41, s41, s45
	v_cvt_pk_bf16_f32 v48, v14, v14
	v_cvt_pk_bf16_f32 v49, v15, v15
	global_store_short v13, v48, s[42:43] offset:512
	global_store_short v13, v49, s[42:43] offset:640
	s_add_u32 s42, s42, s44
	s_addc_u32 s43, s43, s45
	v_mul_f32_e32 v50, v6, v14
	v_mul_f32_e32 v51, v6, v15
	v_fma_f32 v52, v4, v14, -v51
	v_fma_f32 v53, v4, v15, v50
	s_waitcnt vmcnt(62)
	v_add_f32_e32 v14, v52, v18
	v_add_f32_e32 v15, v53, v19
	global_load_dword v18, v12, s[40:41]
	global_load_dword v19, v12, s[40:41] offset:256
	s_add_u32 s40, s40, s44
	s_addc_u32 s41, s41, s45
	v_cvt_pk_bf16_f32 v48, v14, v14
	v_cvt_pk_bf16_f32 v49, v15, v15
	global_store_short v13, v48, s[42:43] offset:512
	global_store_short v13, v49, s[42:43] offset:640
	s_add_u32 s42, s42, s44
	s_addc_u32 s43, s43, s45
	v_mul_f32_e32 v50, v6, v14
	v_mul_f32_e32 v51, v6, v15
	v_fma_f32 v52, v4, v14, -v51
	v_fma_f32 v53, v4, v15, v50
	s_waitcnt vmcnt(62)
	v_add_f32_e32 v14, v52, v20
	v_add_f32_e32 v15, v53, v21
	global_load_dword v20, v12, s[40:41]
	global_load_dword v21, v12, s[40:41] offset:256
	s_add_u32 s40, s40, s44
	s_addc_u32 s41, s41, s45
	v_cvt_pk_bf16_f32 v48, v14, v14
	v_cvt_pk_bf16_f32 v49, v15, v15
	global_store_short v13, v48, s[42:43] offset:512
	global_store_short v13, v49, s[42:43] offset:640
	s_add_u32 s42, s42, s44
	s_addc_u32 s43, s43, s45
	v_mul_f32_e32 v50, v6, v14
	v_mul_f32_e32 v51, v6, v15
	v_fma_f32 v52, v4, v14, -v51
	v_fma_f32 v53, v4, v15, v50
	s_waitcnt vmcnt(62)
	v_add_f32_e32 v14, v52, v22
	v_add_f32_e32 v15, v53, v23
	global_load_dword v22, v12, s[40:41]
	global_load_dword v23, v12, s[40:41] offset:256
	s_add_u32 s40, s40, s44
	s_addc_u32 s41, s41, s45
	v_cvt_pk_bf16_f32 v48, v14, v14
	v_cvt_pk_bf16_f32 v49, v15, v15
	global_store_short v13, v48, s[42:43] offset:512
	global_store_short v13, v49, s[42:43] offset:640
	s_add_u32 s42, s42, s44
	s_addc_u32 s43, s43, s45
	v_mul_f32_e32 v50, v6, v14
	v_mul_f32_e32 v51, v6, v15
	v_fma_f32 v52, v4, v14, -v51
	v_fma_f32 v53, v4, v15, v50
	s_waitcnt vmcnt(62)
	v_add_f32_e32 v14, v52, v24
	v_add_f32_e32 v15, v53, v25
	global_load_dword v24, v12, s[40:41]
	global_load_dword v25, v12, s[40:41] offset:256
	s_add_u32 s40, s40, s44
	s_addc_u32 s41, s41, s45
	v_cvt_pk_bf16_f32 v48, v14, v14
	v_cvt_pk_bf16_f32 v49, v15, v15
	global_store_short v13, v48, s[42:43] offset:512
	global_store_short v13, v49, s[42:43] offset:640
	s_add_u32 s42, s42, s44
	s_addc_u32 s43, s43, s45
	v_mul_f32_e32 v50, v6, v14
	v_mul_f32_e32 v51, v6, v15
	v_fma_f32 v52, v4, v14, -v51
	v_fma_f32 v53, v4, v15, v50
	s_waitcnt vmcnt(62)
	v_add_f32_e32 v14, v52, v26
	v_add_f32_e32 v15, v53, v27
	global_load_dword v26, v12, s[40:41]
	global_load_dword v27, v12, s[40:41] offset:256
	s_add_u32 s40, s40, s44
	s_addc_u32 s41, s41, s45
	v_cvt_pk_bf16_f32 v48, v14, v14
	v_cvt_pk_bf16_f32 v49, v15, v15
	global_store_short v13, v48, s[42:43] offset:512
	global_store_short v13, v49, s[42:43] offset:640
	s_add_u32 s42, s42, s44
	s_addc_u32 s43, s43, s45
	v_mul_f32_e32 v50, v6, v14
	v_mul_f32_e32 v51, v6, v15
	v_fma_f32 v52, v4, v14, -v51
	v_fma_f32 v53, v4, v15, v50
	s_waitcnt vmcnt(62)
	v_add_f32_e32 v14, v52, v28
	v_add_f32_e32 v15, v53, v29
	global_load_dword v28, v12, s[40:41]
	global_load_dword v29, v12, s[40:41] offset:256
	s_add_u32 s40, s40, s44
	s_addc_u32 s41, s41, s45
	v_cvt_pk_bf16_f32 v48, v14, v14
	v_cvt_pk_bf16_f32 v49, v15, v15
	global_store_short v13, v48, s[42:43] offset:512
	global_store_short v13, v49, s[42:43] offset:640
	s_add_u32 s42, s42, s44
	s_addc_u32 s43, s43, s45
	v_mul_f32_e32 v50, v6, v14
	v_mul_f32_e32 v51, v6, v15
	v_fma_f32 v52, v4, v14, -v51
	v_fma_f32 v53, v4, v15, v50
	s_waitcnt vmcnt(62)
	v_add_f32_e32 v14, v52, v30
	v_add_f32_e32 v15, v53, v31
	global_load_dword v30, v12, s[40:41]
	global_load_dword v31, v12, s[40:41] offset:256
	s_add_u32 s40, s40, s44
	s_addc_u32 s41, s41, s45
	v_cvt_pk_bf16_f32 v48, v14, v14
	v_cvt_pk_bf16_f32 v49, v15, v15
	global_store_short v13, v48, s[42:43] offset:512
	global_store_short v13, v49, s[42:43] offset:640
	s_add_u32 s42, s42, s44
	s_addc_u32 s43, s43, s45
	v_mul_f32_e32 v50, v6, v14
	v_mul_f32_e32 v51, v6, v15
	v_fma_f32 v52, v4, v14, -v51
	v_fma_f32 v53, v4, v15, v50
	s_waitcnt vmcnt(62)
; __device__ __forceinline__ unsigned cvt_pk_bf16(float lo, float hi) { const f32x2 v = {lo, hi}; const bf16x2_t b = __builtin_convertvector(v, bf16x2_t); return __builtin_bit_cast(unsigned, b); }
; #define Sb WSP(float, WS_H)
; __global__ void __launch_bounds__(NTHREADS, 2) mega(Args a) {
;     ...
;                 for (int it = wave * G + bx; it < nitem; it += NGW) {
;                     const int dir = it & 1, g = (it >> 1) & 31, b = it >> 6;
;                     const float ar = A16[((g * 2 + dir) * 64 + lane) * 2], ai = A16[((g * 2 + dir) * 64 + lane) * 2 + 1];
;                     float hr = 0.f, hi = 0.f;
;                     const size_t rbase = (size_t)g * NROW + (size_t)b * NC;
;                     for (int c0 = 0; c0 < NC; c0 += 16) {
;                         float sr[16], si[16];
; #pragma unroll
;                         for (int e = 0; e < 16; ++e) { const int c = dir ? NC - 1 - (c0 + e) : c0 + e; const float* sp = Sb + (rbase + c) * 256 + dir * 128 + lane; sr[e] = sp[0]; si[e] = sp[64]; }
; #pragma unroll
;                         for (int e = 0; e < 16; ++e) { const int c = dir ? NC - 1 - (c0 + e) : c0 + e; bf16_t* hp = SSMA + (rbase + c) * 512 + 256 + dir * 128 + lane;
;                             hp[0] = (bf16_t)(cvt_pk_bf16(hr, 0.f) & 0xffffu); hp[64] = (bf16_t)(cvt_pk_bf16(hi, 0.f) & 0xffffu);
;                             const float t = ar * hr - ai * hi + sr[e]; hi = ar * hi + ai * hr + si[e]; hr = t; }
;                     }
;                 }
	v_add_f32_e32 v14, v52, v32
	v_add_f32_e32 v15, v53, v33
	global_load_dword v32, v12, s[40:41]
	global_load_dword v33, v12, s[40:41] offset:256
	s_add_u32 s40, s40, s44
	s_addc_u32 s41, s41, s45
	v_cvt_pk_bf16_f32 v48, v14, v14
	v_cvt_pk_bf16_f32 v49, v15, v15
	global_store_short v13, v48, s[42:43] offset:512
	global_store_short v13, v49, s[42:43] offset:640
	s_add_u32 s42, s42, s44
	s_addc_u32 s43, s43, s45
	v_mul_f32_e32 v50, v6, v14
	v_mul_f32_e32 v51, v6, v15
	v_fma_f32 v52, v4, v14, -v51
	v_fma_f32 v53, v4, v15, v50
	s_waitcnt vmcnt(62)
	v_add_f32_e32 v14, v52, v34
	v_add_f32_e32 v15, v53, v35
	global_load_dword v34, v12, s[40:41]
	global_load_dword v35, v12, s[40:41] offset:256
	s_add_u32 s40, s40, s44
	s_addc_u32 s41, s41, s45
	v_cvt_pk_bf16_f32 v48, v14, v14
	v_cvt_pk_bf16_f32 v49, v15, v15
	global_store_short v13, v48, s[42:43] offset:512
	global_store_short v13, v49, s[42:43] offset:640
	s_add_u32 s42, s42, s44
	s_addc_u32 s43, s43, s45
	v_mul_f32_e32 v50, v6, v14
	v_mul_f32_e32 v51, v6, v15
	v_fma_f32 v52, v4, v14, -v51
	v_fma_f32 v53, v4, v15, v50
	s_waitcnt vmcnt(62)
	v_add_f32_e32 v14, v52, v36
	v_add_f32_e32 v15, v53, v37
	global_load_dword v36, v12, s[40:41]
	global_load_dword v37, v12, s[40:41] offset:256
	s_add_u32 s40, s40, s44
	s_addc_u32 s41, s41, s45
	v_cvt_pk_bf16_f32 v48, v14, v14
	v_cvt_pk_bf16_f32 v49, v15, v15
	global_store_short v13, v48, s[42:43] offset:512
	global_store_short v13, v49, s[42:43] offset:640
	s_add_u32 s42, s42, s44
	s_addc_u32 s43, s43, s45
	v_mul_f32_e32 v50, v6, v14
	v_mul_f32_e32 v51, v6, v15
	v_fma_f32 v52, v4, v14, -v51
	v_fma_f32 v53, v4, v15, v50
	s_waitcnt vmcnt(62)
	v_add_f32_e32 v14, v52, v38
	v_add_f32_e32 v15, v53, v39
	global_load_dword v38, v12, s[40:41]
	global_load_dword v39, v12, s[40:41] offset:256
	s_add_u32 s40, s40, s44
	s_addc_u32 s41, s41, s45
	v_cvt_pk_bf16_f32 v48, v14, v14
	v_cvt_pk_bf16_f32 v49, v15, v15
	global_store_short v13, v48, s[42:43] offset:512
	global_store_short v13, v49, s[42:43] offset:640
	s_add_u32 s42, s42, s44
	s_addc_u32 s43, s43, s45
	v_mul_f32_e32 v50, v6, v14
	v_mul_f32_e32 v51, v6, v15
	v_fma_f32 v52, v4, v14, -v51
	v_fma_f32 v53, v4, v15, v50
	s_waitcnt vmcnt(62)
	v_add_f32_e32 v14, v52, v40
	v_add_f32_e32 v15, v53, v41
	global_load_dword v40, v12, s[40:41]
	global_load_dword v41, v12, s[40:41] offset:256
	s_add_u32 s40, s40, s44
	s_addc_u32 s41, s41, s45
	v_cvt_pk_bf16_f32 v48, v14, v14
	v_cvt_pk_bf16_f32 v49, v15, v15
	global_store_short v13, v48, s[42:43] offset:512
	global_store_short v13, v49, s[42:43] offset:640
	s_add_u32 s42, s42, s44
	s_addc_u32 s43, s43, s45
	v_mul_f32_e32 v50, v6, v14
	v_mul_f32_e32 v51, v6, v15
	v_fma_f32 v52, v4, v14, -v51
	v_fma_f32 v53, v4, v15, v50
	s_waitcnt vmcnt(62)
	v_add_f32_e32 v14, v52, v42
	v_add_f32_e32 v15, v53, v43
	global_load_dword v42, v12, s[40:41]
	global_load_dword v43, v12, s[40:41] offset:256
	s_add_u32 s40, s40, s44
	s_addc_u32 s41, s41, s45
	v_cvt_pk_bf16_f32 v48, v14, v14
	v_cvt_pk_bf16_f32 v49, v15, v15
	global_store_short v13, v48, s[42:43] offset:512
	global_store_short v13, v49, s[42:43] offset:640
	s_add_u32 s42, s42, s44
	s_addc_u32 s43, s43, s45
	v_mul_f32_e32 v50, v6, v14
	v_mul_f32_e32 v51, v6, v15
	v_fma_f32 v52, v4, v14, -v51
	v_fma_f32 v53, v4, v15, v50
	s_waitcnt vmcnt(62)
	v_add_f32_e32 v14, v52, v44
	v_add_f32_e32 v15, v53, v45
	global_load_dword v44, v12, s[40:41]
	global_load_dword v45, v12, s[40:41] offset:256
	s_add_u32 s40, s40, s44
	s_addc_u32 s41, s41, s45
	v_cvt_pk_bf16_f32 v48, v14, v14
	v_cvt_pk_bf16_f32 v49, v15, v15
	global_store_short v13, v48, s[42:43] offset:512
	global_store_short v13, v49, s[42:43] offset:640
	s_add_u32 s42, s42, s44
	s_addc_u32 s43, s43, s45
	v_mul_f32_e32 v50, v6, v14
	v_mul_f32_e32 v51, v6, v15
	v_fma_f32 v52, v4, v14, -v51
	v_fma_f32 v53, v4, v15, v50
	s_waitcnt vmcnt(62)
	v_add_f32_e32 v14, v52, v46
	v_add_f32_e32 v15, v53, v47
	global_load_dword v46, v12, s[40:41]
	global_load_dword v47, v12, s[40:41] offset:256
	s_add_u32 s40, s40, s44
	s_addc_u32 s41, s41, s45
	s_sub_u32 s46, s46, 1
	s_cmp_lg_u32 s46, 0
	s_cbranch_scc1 .Lscan_loop
.Lscan_done:
	s_waitcnt vmcnt(0)
	v_readlane_b32 s2, v253, 32
	s_add_i32 s74, s74, s2
	s_cmp_ge_i32 s74, s36
	v_readlane_b32 s3, v253, 33
	s_cbranch_scc0 .LBB0_507
